# MLA loops: scalar-base LDS-DMA addressing (SGPR stream pointers + invariant 32-bit lane offsets), no per-step 64-bit VALU address math
# baseline (speedup 1.0000x reference)
; #define AT_MASK(S0, S1, tt) do { if (SWA) { const int kb_ = (tt) * 64 + 8 * hi - qrel; _Pragma("unroll") for (int r = 0; r < 16; ++r) { const int d_ = kb_ + 16 * (r >> 3) + (r & 7); \
;         if (d_ < -128 || d_ > 128) S0[r] = -1e30f; if (d_ + 32 < -128 || d_ + 32 > 128) S1[r] = -1e30f; } } } while (0)
; template <bool SWA> ...
;     ...
;     const int koff = pkey * ldk + 8 * wv, voff = lane * T + 8 * wv, roff = pkey * 512 + 8 * (wv & 3);
;     const bool do_r = (!SWA) && wv < 4;
;     const int kfo = hi * 1024 + l32 * 16, vfo = AT_KB + hi * 1024 + l32 * 16;
;     ...
;     AT_GLOAD(0, 0); AT_GLOAD(1, AT_BUF);
;     asm volatile("s_waitcnt vmcnt(0)" ::: "memory");
;     __syncthreads();
;     f32x16 o0, o1, negm;
;     float mref = SWA ? m_init : 0.f, lrun = l_init;
; #pragma unroll
;     for (int r = 0; r < 16; ++r) { o0[r] = 0.f; o1[r] = 0.f; negm[r] = -mref; }
;     f32x16 sA0, sA1, sB0, sB1;
;     ...
;     {
;         const unsigned char* Bn = lds;
;         sA0 = __builtin_amdgcn_mfma_f32_32x32x16_bf16(*(const bf16x8*)(Bn + kfo), qf[0], negm, 0, 0, 0);
;         sA1 = __builtin_amdgcn_mfma_f32_32x32x16_bf16(*(const bf16x8*)(Bn + kfo + 512), qf[0], negm, 0, 0, 0);
; #pragma unroll
;         for (int d0 = 1; d0 < ND; ++d0) { sA0 = __builtin_amdgcn_mfma_f32_32x32x16_bf16(*(const bf16x8*)(Bn + kfo + 2048 * d0), qf[d0], sA0, 0, 0, 0);
;             sA1 = __builtin_amdgcn_mfma_f32_32x32x16_bf16(*(const bf16x8*)(Bn + kfo + 512 + 2048 * d0), qf[d0], sA1, 0, 0, 0); }
;         AT_MASK(sA0, sA1, 0);
;     }
;     int bt = 0, bn = AT_BUF, bw = 2 * AT_BUF;
.LBB0_1008:
	s_lshr_b32 s6, s12, 5
	s_and_b32 s6, s6, 7
	s_lshl_b32 s15, s6, 7
	s_lshl_b32 s19, s6, 22
	s_lshl_b64 s[6:7], s[4:5], 23
	v_add_u32_e32 v6, s18, v236
	s_lshl_b32 s13, s13, 6
	v_lshl_or_b32 v206, v6, 1, s6
	s_or_b32 s6, s6, s15
	s_lshl_b64 s[4:5], s[4:5], 14
	s_add_u32 s4, s19, s4
	v_mov_b32_e32 v6, s6
	v_mov_b32_e32 v7, s7
	s_addc_u32 s5, 0, s5
	v_mov_b32_e32 v16, v1
	v_mov_b32_e32 v17, v1
	v_lshl_add_u64 v[208:209], v[4:5], 1, v[6:7]
	v_lshl_add_u64 v[210:211], v[2:3], 1, s[4:5]
	v_mov_b32_e32 v2, v1
	v_mov_b32_e32 v3, v1
	v_mov_b32_e32 v4, v1
	v_mov_b32_e32 v5, v1
	v_mov_b32_e32 v6, v1
	v_mov_b32_e32 v7, v1
	v_mov_b32_e32 v8, v1
	v_mov_b32_e32 v9, v1
	v_mov_b32_e32 v10, v1
	v_mov_b32_e32 v11, v1
	v_mov_b32_e32 v12, v1
	v_mov_b32_e32 v13, v1
	v_mov_b32_e32 v14, v1
	v_mov_b32_e32 v15, v1
	v_bfrev_b32_e32 v82, 1
	v_mov_b64_e32 v[32:33], v[16:17]
	v_readlane_b32 s36, v254, 54
	v_mov_b32_e32 v207, s7
	s_mov_b32 s4, 0
	s_mov_b32 s18, 0xa000
	s_movk_i32 s15, 0x5000
	v_mov_b32_e32 v239, 0
	s_mov_b32 s19, -2
	v_mov_b64_e32 v[30:31], v[14:15]
	v_mov_b64_e32 v[28:29], v[12:13]
	v_mov_b64_e32 v[26:27], v[10:11]
	v_mov_b64_e32 v[24:25], v[8:9]
	v_mov_b64_e32 v[22:23], v[6:7]
	v_mov_b64_e32 v[20:21], v[4:5]
	v_mov_b64_e32 v[18:19], v[2:3]
	v_mov_b32_e32 v170, 0
	v_mov_b32_e32 v83, v82
	v_mov_b32_e32 v84, v82
	v_mov_b32_e32 v85, v82
	v_mov_b32_e32 v86, v82
	v_mov_b32_e32 v87, v82
	v_mov_b32_e32 v88, v82
	v_mov_b32_e32 v89, v82
	v_mov_b32_e32 v90, v82
	v_mov_b32_e32 v91, v82
	v_mov_b32_e32 v92, v82
	v_mov_b32_e32 v93, v82
	v_mov_b32_e32 v94, v82
	v_mov_b32_e32 v95, v82
	v_mov_b32_e32 v96, v82
	v_mov_b32_e32 v97, v82
	v_readlane_b32 s38, v254, 56
	v_readlane_b32 s39, v254, 57
	v_readlane_b32 s37, v254, 55
	s_mov_b32 s20, 0xf000
	v_readfirstlane_b32 s6, v208
	v_readfirstlane_b32 s7, v209
	v_readfirstlane_b32 s24, v210
	v_readfirstlane_b32 s25, v211
	s_add_u32 s34, s38, s6
	s_addc_u32 s35, s39, s7
	s_add_u32 s34, s34, 0x17020000
	s_addc_u32 s35, s35, 0
	v_subrev_u32_e32 v154, s6, v208
	s_add_u32 s28, s38, s24
	s_addc_u32 s29, s39, s25
	s_add_u32 s28, s28, 0x18008100
	s_addc_u32 s29, s29, 0
	v_subrev_u32_e32 v156, s24, v210
	v_readfirstlane_b32 s6, v206
	v_readfirstlane_b32 s7, v207
	s_nop 1
	s_add_u32 s38, s38, s6
	s_addc_u32 s39, s39, s7
	s_add_u32 s38, s38, 0x8820300
	s_addc_u32 s39, s39, 0
	v_subrev_u32_e32 v158, s6, v206
	s_add_i32 s24, s14, s18
	s_mov_b32 m0, s24
	s_andn2_b64 vcc, exec, s[16:17]
	global_load_lds_dwordx4 v154, s[34:35]
	s_add_i32 m0, s24, 0x3000
	s_nop 0
	global_load_lds_dwordx4 v156, s[28:29]
	s_cbranch_vccnz .LmlaLP_nokr
	s_add_i32 m0, s24, 0x2000
	s_nop 0
	global_load_lds_dwordx4 v158, s[38:39]
.LmlaLP_nokr:
	s_add_u32 s34, s34, 0x10000
	s_addc_u32 s35, s35, 0
	s_add_u32 s28, s28, 0x80
	s_addc_u32 s29, s29, 0
	s_add_u32 s38, s38, 0x10000
	s_addc_u32 s39, s39, 0
	v_max3_f32 v162, v66, v67, v68
	v_max3_f32 v163, v50, v51, v52
	v_max3_f32 v162, v162, v69, v70
	v_max3_f32 v163, v163, v53, v54
	v_max3_f32 v162, v162, v71, v72
	v_max3_f32 v163, v163, v55, v56
	v_max3_f32 v162, v162, v73, v74
	v_max3_f32 v163, v163, v57, v58
	v_max3_f32 v162, v162, v75, v76
	v_max3_f32 v163, v163, v59, v60
	v_max3_f32 v162, v162, v77, v78
	v_max3_f32 v163, v163, v61, v62
	v_max3_f32 v162, v162, v79, v80
	v_max3_f32 v163, v163, v63, v64
	v_max3_f32 v162, v162, v81, v65
	v_max_f32_e32 v162, v162, v163
.LmlaL_top:
	v_add_u32_e32 v164, s15, v238
	v_add_u32_e32 v165, s4, v238
	ds_read_b128 v[172:175], v164
	ds_read_b128 v[176:179], v164 offset:512
	ds_read_b128 v[180:183], v164 offset:2048
	ds_read_b128 v[184:187], v164 offset:2560
	ds_read_b128 v[188:191], v164 offset:4096
	s_add_i32 s24, s14, s20
	s_mov_b32 m0, s24
	s_andn2_b64 vcc, exec, s[16:17]
	global_load_lds_dwordx4 v154, s[34:35]
	s_add_i32 m0, s24, 0x3000
	s_nop 0
	global_load_lds_dwordx4 v156, s[28:29]
	s_cbranch_vccnz .LmlaLA_nokr
	s_add_i32 m0, s24, 0x2000
	s_nop 0
	global_load_lds_dwordx4 v158, s[38:39]
.LmlaLA_nokr:
	s_add_u32 s34, s34, 0x10000
	s_addc_u32 s35, s35, 0
	s_add_u32 s28, s28, 0x80
	s_addc_u32 s29, s29, 0
	s_add_u32 s38, s38, 0x10000
	s_addc_u32 s39, s39, 0
	s_cmp_eq_u32 s19, -2
	s_cselect_b64 s[6:7], -1, 0
	v_cmp_lt_f32_e32 vcc, s33, v162
	s_or_b64 vcc, s[6:7], vcc
	s_cbranch_vccz .LmlaLA_common
	v_mov_b32_e32 v163, v162
	s_nop 1
	v_permlane32_swap_b32_e32 v162, v163
	v_max_f32_e32 v162, v162, v163
	v_max_f32_e32 v220, 0, v162
	v_cndmask_b32_e64 v220, v220, v162, s[6:7]
	v_exp_f32_e64 v222, -v220
	v_add_f32_e32 v239, v239, v220
	v_pk_add_f32 v[66:67], v[66:67], v[220:221] op_sel_hi:[1,0] neg_lo:[0,1] neg_hi:[0,1]
	v_pk_add_f32 v[68:69], v[68:69], v[220:221] op_sel_hi:[1,0] neg_lo:[0,1] neg_hi:[0,1]
	v_pk_add_f32 v[70:71], v[70:71], v[220:221] op_sel_hi:[1,0] neg_lo:[0,1] neg_hi:[0,1]
	v_pk_add_f32 v[72:73], v[72:73], v[220:221] op_sel_hi:[1,0] neg_lo:[0,1] neg_hi:[0,1]
	v_pk_add_f32 v[74:75], v[74:75], v[220:221] op_sel_hi:[1,0] neg_lo:[0,1] neg_hi:[0,1]
	v_pk_add_f32 v[76:77], v[76:77], v[220:221] op_sel_hi:[1,0] neg_lo:[0,1] neg_hi:[0,1]
	v_pk_add_f32 v[78:79], v[78:79], v[220:221] op_sel_hi:[1,0] neg_lo:[0,1] neg_hi:[0,1]
	v_pk_add_f32 v[80:81], v[80:81], v[220:221] op_sel_hi:[1,0] neg_lo:[0,1] neg_hi:[0,1]
	v_pk_add_f32 v[50:51], v[50:51], v[220:221] op_sel_hi:[1,0] neg_lo:[0,1] neg_hi:[0,1]
	v_pk_add_f32 v[52:53], v[52:53], v[220:221] op_sel_hi:[1,0] neg_lo:[0,1] neg_hi:[0,1]
	v_pk_add_f32 v[54:55], v[54:55], v[220:221] op_sel_hi:[1,0] neg_lo:[0,1] neg_hi:[0,1]
	v_pk_add_f32 v[56:57], v[56:57], v[220:221] op_sel_hi:[1,0] neg_lo:[0,1] neg_hi:[0,1]
	v_pk_add_f32 v[58:59], v[58:59], v[220:221] op_sel_hi:[1,0] neg_lo:[0,1] neg_hi:[0,1]
	v_pk_add_f32 v[60:61], v[60:61], v[220:221] op_sel_hi:[1,0] neg_lo:[0,1] neg_hi:[0,1]
	v_pk_add_f32 v[62:63], v[62:63], v[220:221] op_sel_hi:[1,0] neg_lo:[0,1] neg_hi:[0,1]
	v_pk_add_f32 v[64:65], v[64:65], v[220:221] op_sel_hi:[1,0] neg_lo:[0,1] neg_hi:[0,1]
	v_pk_mul_f32 v[2:3], v[2:3], v[222:223] op_sel_hi:[1,0]
	v_pk_mul_f32 v[4:5], v[4:5], v[222:223] op_sel_hi:[1,0]
	v_pk_mul_f32 v[6:7], v[6:7], v[222:223] op_sel_hi:[1,0]
	v_pk_mul_f32 v[8:9], v[8:9], v[222:223] op_sel_hi:[1,0]
	v_pk_mul_f32 v[10:11], v[10:11], v[222:223] op_sel_hi:[1,0]
	v_pk_mul_f32 v[12:13], v[12:13], v[222:223] op_sel_hi:[1,0]
	v_pk_mul_f32 v[14:15], v[14:15], v[222:223] op_sel_hi:[1,0]
	v_pk_mul_f32 v[16:17], v[16:17], v[222:223] op_sel_hi:[1,0]
	v_pk_mul_f32 v[18:19], v[18:19], v[222:223] op_sel_hi:[1,0]
	v_pk_mul_f32 v[20:21], v[20:21], v[222:223] op_sel_hi:[1,0]
	v_pk_mul_f32 v[22:23], v[22:23], v[222:223] op_sel_hi:[1,0]
	v_pk_mul_f32 v[24:25], v[24:25], v[222:223] op_sel_hi:[1,0]
	v_pk_mul_f32 v[26:27], v[26:27], v[222:223] op_sel_hi:[1,0]
	v_pk_mul_f32 v[28:29], v[28:29], v[222:223] op_sel_hi:[1,0]
	v_pk_mul_f32 v[30:31], v[30:31], v[222:223] op_sel_hi:[1,0]
	v_pk_mul_f32 v[32:33], v[32:33], v[222:223] op_sel_hi:[1,0]
	v_mul_f32_e32 v170, v170, v222
	v_xor_b32_e32 v82, 0x80000000, v239
	v_mov_b32_e32 v83, v82
	v_mov_b32_e32 v84, v82
	v_mov_b32_e32 v85, v82
	v_mov_b32_e32 v86, v82
	v_mov_b32_e32 v87, v82
	v_mov_b32_e32 v88, v82
	v_mov_b32_e32 v89, v82
	v_mov_b32_e32 v90, v82
	v_mov_b32_e32 v91, v82
	v_mov_b32_e32 v92, v82
	v_mov_b32_e32 v93, v82
	v_mov_b32_e32 v94, v82
	v_mov_b32_e32 v95, v82
	v_mov_b32_e32 v96, v82
	v_mov_b32_e32 v97, v82
	s_nop 1

.LmlaLA_wd:
	s_barrier
	v_add_u32_e32 v164, s18, v238
	v_add_u32_e32 v165, s15, v238
	ds_read_b128 v[172:175], v164
	ds_read_b128 v[176:179], v164 offset:512
	ds_read_b128 v[180:183], v164 offset:2048
	ds_read_b128 v[184:187], v164 offset:2560
	ds_read_b128 v[188:191], v164 offset:4096
	s_add_i32 s24, s14, s4
	s_mov_b32 m0, s24
	s_andn2_b64 vcc, exec, s[16:17]
	global_load_lds_dwordx4 v154, s[34:35]
	s_add_i32 m0, s24, 0x3000
	s_nop 0
	global_load_lds_dwordx4 v156, s[28:29]
	s_cbranch_vccnz .LmlaLB_nokr
	s_add_i32 m0, s24, 0x2000
	s_nop 0
	global_load_lds_dwordx4 v158, s[38:39]
.LmlaLB_nokr:
	s_add_u32 s34, s34, 0x10000
	s_addc_u32 s35, s35, 0
	s_add_u32 s28, s28, 0x80
	s_addc_u32 s29, s29, 0
	s_add_u32 s38, s38, 0x10000
	s_addc_u32 s39, s39, 0
	v_cmp_lt_f32_e32 vcc, s33, v162
	s_cbranch_vccz .LmlaLB_common
	v_mov_b32_e32 v163, v162
	s_nop 1
	v_permlane32_swap_b32_e32 v162, v163
	v_max_f32_e32 v162, v162, v163
	v_max_f32_e32 v220, 0, v162
	v_exp_f32_e64 v222, -v220
	v_add_f32_e32 v239, v239, v220
	v_pk_add_f32 v[98:99], v[98:99], v[220:221] op_sel_hi:[1,0] neg_lo:[0,1] neg_hi:[0,1]
	v_pk_add_f32 v[100:101], v[100:101], v[220:221] op_sel_hi:[1,0] neg_lo:[0,1] neg_hi:[0,1]
	v_pk_add_f32 v[102:103], v[102:103], v[220:221] op_sel_hi:[1,0] neg_lo:[0,1] neg_hi:[0,1]
	v_pk_add_f32 v[104:105], v[104:105], v[220:221] op_sel_hi:[1,0] neg_lo:[0,1] neg_hi:[0,1]
	v_pk_add_f32 v[106:107], v[106:107], v[220:221] op_sel_hi:[1,0] neg_lo:[0,1] neg_hi:[0,1]
	v_pk_add_f32 v[108:109], v[108:109], v[220:221] op_sel_hi:[1,0] neg_lo:[0,1] neg_hi:[0,1]
	v_pk_add_f32 v[110:111], v[110:111], v[220:221] op_sel_hi:[1,0] neg_lo:[0,1] neg_hi:[0,1]
	v_pk_add_f32 v[112:113], v[112:113], v[220:221] op_sel_hi:[1,0] neg_lo:[0,1] neg_hi:[0,1]
	v_pk_add_f32 v[114:115], v[114:115], v[220:221] op_sel_hi:[1,0] neg_lo:[0,1] neg_hi:[0,1]
	v_pk_add_f32 v[116:117], v[116:117], v[220:221] op_sel_hi:[1,0] neg_lo:[0,1] neg_hi:[0,1]
	v_pk_add_f32 v[118:119], v[118:119], v[220:221] op_sel_hi:[1,0] neg_lo:[0,1] neg_hi:[0,1]
	v_pk_add_f32 v[120:121], v[120:121], v[220:221] op_sel_hi:[1,0] neg_lo:[0,1] neg_hi:[0,1]
	v_pk_add_f32 v[122:123], v[122:123], v[220:221] op_sel_hi:[1,0] neg_lo:[0,1] neg_hi:[0,1]
	v_pk_add_f32 v[124:125], v[124:125], v[220:221] op_sel_hi:[1,0] neg_lo:[0,1] neg_hi:[0,1]
	v_pk_add_f32 v[126:127], v[126:127], v[220:221] op_sel_hi:[1,0] neg_lo:[0,1] neg_hi:[0,1]
	v_pk_add_f32 v[128:129], v[128:129], v[220:221] op_sel_hi:[1,0] neg_lo:[0,1] neg_hi:[0,1]
	v_pk_mul_f32 v[2:3], v[2:3], v[222:223] op_sel_hi:[1,0]
	v_pk_mul_f32 v[4:5], v[4:5], v[222:223] op_sel_hi:[1,0]
	v_pk_mul_f32 v[6:7], v[6:7], v[222:223] op_sel_hi:[1,0]
	v_pk_mul_f32 v[8:9], v[8:9], v[222:223] op_sel_hi:[1,0]
	v_pk_mul_f32 v[10:11], v[10:11], v[222:223] op_sel_hi:[1,0]
	v_pk_mul_f32 v[12:13], v[12:13], v[222:223] op_sel_hi:[1,0]
	v_pk_mul_f32 v[14:15], v[14:15], v[222:223] op_sel_hi:[1,0]
	v_pk_mul_f32 v[16:17], v[16:17], v[222:223] op_sel_hi:[1,0]
	v_pk_mul_f32 v[18:19], v[18:19], v[222:223] op_sel_hi:[1,0]
	v_pk_mul_f32 v[20:21], v[20:21], v[222:223] op_sel_hi:[1,0]
	v_pk_mul_f32 v[22:23], v[22:23], v[222:223] op_sel_hi:[1,0]
	v_pk_mul_f32 v[24:25], v[24:25], v[222:223] op_sel_hi:[1,0]
	v_pk_mul_f32 v[26:27], v[26:27], v[222:223] op_sel_hi:[1,0]
	v_pk_mul_f32 v[28:29], v[28:29], v[222:223] op_sel_hi:[1,0]
	v_pk_mul_f32 v[30:31], v[30:31], v[222:223] op_sel_hi:[1,0]
	v_pk_mul_f32 v[32:33], v[32:33], v[222:223] op_sel_hi:[1,0]
	v_mul_f32_e32 v170, v170, v222
	v_xor_b32_e32 v82, 0x80000000, v239
	v_mov_b32_e32 v83, v82
	v_mov_b32_e32 v84, v82
	v_mov_b32_e32 v85, v82
	v_mov_b32_e32 v86, v82
	v_mov_b32_e32 v87, v82
	v_mov_b32_e32 v88, v82
	v_mov_b32_e32 v89, v82
	v_mov_b32_e32 v90, v82
	v_mov_b32_e32 v91, v82
	v_mov_b32_e32 v92, v82
	v_mov_b32_e32 v93, v82
	v_mov_b32_e32 v94, v82
	v_mov_b32_e32 v95, v82
	v_mov_b32_e32 v96, v82
	v_mov_b32_e32 v97, v82
	s_nop 1
.LmlaLB_common:
	s_waitcnt lgkmcnt(4)
	v_mfma_f32_32x32x16_bf16 v[66:81], v[172:175], v[150:153], v[82:97]
	ds_read_b128 v[192:195], v164 offset:4608
	v_exp_f32_e32 v98, v98
	v_exp_f32_e32 v99, v99
	v_exp_f32_e32 v100, v100
	s_waitcnt lgkmcnt(4)
	v_mfma_f32_32x32x16_bf16 v[50:65], v[176:179], v[150:153], v[82:97]
	ds_read_b128 v[240:243], v164 offset:6144
	v_exp_f32_e32 v101, v101
	v_exp_f32_e32 v102, v102
	v_exp_f32_e32 v103, v103
	s_waitcnt lgkmcnt(4)
	v_mfma_f32_32x32x16_bf16 v[66:81], v[180:183], v[134:137], v[66:81]
	ds_read_b128 v[244:247], v164 offset:6656
	v_exp_f32_e32 v104, v104
	v_exp_f32_e32 v105, v105
	v_cvt_pk_bf16_f32 v34, v98, v99
	v_cvt_pk_bf16_f32 v35, v100, v101
	s_waitcnt lgkmcnt(4)
	v_mfma_f32_32x32x16_bf16 v[50:65], v[184:187], v[134:137], v[50:65]
	ds_read_b128 v[248:251], v164 offset:8192
	v_exp_f32_e32 v106, v106
	v_exp_f32_e32 v107, v107
	v_cvt_pk_bf16_f32 v36, v102, v103
	v_cvt_pk_bf16_f32 v37, v104, v105
	s_waitcnt lgkmcnt(4)
	v_mfma_f32_32x32x16_bf16 v[66:81], v[188:191], v[138:141], v[66:81]
	ds_read_b128 v[172:175], v164 offset:8704
	v_exp_f32_e32 v108, v108
	v_exp_f32_e32 v109, v109
	v_exp_f32_e32 v110, v110
	s_waitcnt lgkmcnt(4)
	v_mfma_f32_32x32x16_bf16 v[50:65], v[192:195], v[138:141], v[50:65]
	ds_read_b128 v[176:179], v164 offset:10240
	v_exp_f32_e32 v111, v111
	v_exp_f32_e32 v112, v112
	v_exp_f32_e32 v113, v113
	s_waitcnt lgkmcnt(4)
	v_mfma_f32_32x32x16_bf16 v[66:81], v[240:243], v[142:145], v[66:81]
	ds_read_b128 v[180:183], v164 offset:10752
	v_exp_f32_e32 v114, v114
	v_exp_f32_e32 v115, v115
	v_cvt_pk_bf16_f32 v38, v106, v107
	v_cvt_pk_bf16_f32 v39, v108, v109
	s_waitcnt lgkmcnt(4)
	v_mfma_f32_32x32x16_bf16 v[50:65], v[244:247], v[142:145], v[50:65]
	ds_read_b128 v[184:187], v165 offset:12288
	v_exp_f32_e32 v116, v116
	v_exp_f32_e32 v117, v117
	v_cvt_pk_bf16_f32 v40, v110, v111
	v_cvt_pk_bf16_f32 v41, v112, v113
	s_waitcnt lgkmcnt(4)
	v_mfma_f32_32x32x16_bf16 v[66:81], v[248:251], v[146:149], v[66:81]
	ds_read_b128 v[188:191], v165 offset:12800
	v_exp_f32_e32 v118, v118
	v_exp_f32_e32 v119, v119
	v_exp_f32_e32 v120, v120
	s_waitcnt lgkmcnt(4)
	v_mfma_f32_32x32x16_bf16 v[50:65], v[172:175], v[146:149], v[50:65]
	ds_read_b128 v[192:195], v165 offset:14336
	v_exp_f32_e32 v121, v121
	v_exp_f32_e32 v122, v122
	v_cvt_pk_bf16_f32 v42, v114, v115
	v_cvt_pk_bf16_f32 v43, v116, v117
	s_waitcnt lgkmcnt(4)
	v_mfma_f32_32x32x16_bf16 v[66:81], v[176:179], v[130:133], v[66:81]
	ds_read_b128 v[240:243], v165 offset:14848
	v_exp_f32_e32 v123, v123
	v_exp_f32_e32 v124, v124
	v_cvt_pk_bf16_f32 v44, v118, v119
	v_cvt_pk_bf16_f32 v45, v120, v121
	s_waitcnt lgkmcnt(4)
	v_mfma_f32_32x32x16_bf16 v[50:65], v[180:183], v[130:133], v[50:65]
	ds_read_b128 v[244:247], v165 offset:16384
	v_exp_f32_e32 v125, v125
	v_exp_f32_e32 v126, v126
	v_exp_f32_e32 v127, v127
	s_waitcnt lgkmcnt(4)
	v_mfma_f32_32x32x16_bf16 v[2:17], v[184:187], v[34:37], v[2:17]
	ds_read_b128 v[248:251], v165 offset:16896
	v_exp_f32_e32 v128, v128
	v_exp_f32_e32 v129, v129
	v_cvt_pk_bf16_f32 v46, v122, v123
	v_cvt_pk_bf16_f32 v47, v124, v125
	s_waitcnt lgkmcnt(4)
	v_mfma_f32_32x32x16_bf16 v[18:33], v[188:191], v[34:37], v[18:33]
	ds_read_b128 v[172:175], v165 offset:18432
	v_cvt_pk_bf16_f32 v48, v126, v127
	v_cvt_pk_bf16_f32 v49, v128, v129
	v_add_f32_e32 v166, v98, v99
	v_add_f32_e32 v167, v100, v101
	v_add_f32_e32 v168, v102, v103
	v_add_f32_e32 v169, v104, v105
	s_waitcnt lgkmcnt(4)
	v_mfma_f32_32x32x16_bf16 v[2:17], v[192:195], v[38:41], v[2:17]
	ds_read_b128 v[176:179], v165 offset:18944
	v_add_f32_e32 v166, v166, v106
	v_add_f32_e32 v167, v167, v107
	v_add_f32_e32 v168, v168, v108
	v_add_f32_e32 v169, v169, v109
	v_max3_f32 v162, v66, v67, v68
	v_max3_f32 v163, v50, v51, v52
	s_waitcnt lgkmcnt(4)
	v_mfma_f32_32x32x16_bf16 v[18:33], v[240:243], v[38:41], v[18:33]
	v_add_f32_e32 v166, v166, v110
	v_add_f32_e32 v167, v167, v111
	v_add_f32_e32 v168, v168, v112
	v_add_f32_e32 v169, v169, v113
	v_max3_f32 v162, v162, v69, v70
	v_max3_f32 v163, v163, v53, v54
	s_waitcnt lgkmcnt(3)
	v_mfma_f32_32x32x16_bf16 v[2:17], v[244:247], v[42:45], v[2:17]
	v_add_f32_e32 v166, v166, v114
	v_add_f32_e32 v167, v167, v115
	v_add_f32_e32 v168, v168, v116
	v_add_f32_e32 v169, v169, v117
	v_max3_f32 v162, v162, v71, v72
	v_max3_f32 v163, v163, v55, v56
	s_waitcnt lgkmcnt(2)
	v_mfma_f32_32x32x16_bf16 v[18:33], v[248:251], v[42:45], v[18:33]
	v_add_f32_e32 v166, v166, v118
	v_add_f32_e32 v167, v167, v119
	v_add_f32_e32 v168, v168, v120
	v_add_f32_e32 v169, v169, v121
	v_max3_f32 v162, v162, v73, v74
	v_max3_f32 v163, v163, v57, v58
	s_waitcnt lgkmcnt(1)
	v_mfma_f32_32x32x16_bf16 v[2:17], v[172:175], v[46:49], v[2:17]
	v_add_f32_e32 v166, v166, v122
	v_add_f32_e32 v167, v167, v123
	v_add_f32_e32 v168, v168, v124
	v_add_f32_e32 v169, v169, v125
	v_max3_f32 v162, v162, v75, v76
	v_max3_f32 v163, v163, v59, v60
	s_waitcnt lgkmcnt(0)
	v_mfma_f32_32x32x16_bf16 v[18:33], v[176:179], v[46:49], v[18:33]
	v_add_f32_e32 v166, v166, v126
	v_add_f32_e32 v167, v167, v127
	v_add_f32_e32 v168, v168, v128
	v_add_f32_e32 v169, v169, v129
	v_max3_f32 v162, v162, v77, v78
	v_max3_f32 v163, v163, v61, v62
	v_max3_f32 v162, v162, v79, v80
	v_max3_f32 v163, v163, v63, v64
	v_add_f32_e32 v166, v166, v167
	v_add_f32_e32 v168, v168, v169
	v_add_f32_e32 v166, v166, v168
	v_add_f32_e32 v170, v170, v166
	v_max3_f32 v162, v162, v81, v65
	v_max_f32_e32 v162, v162, v163
	s_add_i32 s19, s19, 2
	s_andn2_b64 vcc, exec, s[16:17]
	s_cbranch_vccnz .LmlaLB_w2
	s_waitcnt vmcnt(3)
	s_branch .LmlaLB_wd

; template <bool SWA> ...
;     ...
;     const int koff = pkey * ldk + 8 * wv, voff = lane * T + 8 * wv, roff = pkey * 512 + 8 * (wv & 3);
;     const bool do_r = (!SWA) && wv < 4;
;     const int kfo = hi * 1024 + l32 * 16, vfo = AT_KB + hi * 1024 + l32 * 16;
;     ...
;     AT_GLOAD(0, 0); AT_GLOAD(1, AT_BUF);
;     asm volatile("s_waitcnt vmcnt(0)" ::: "memory");
;     __syncthreads();
;     f32x16 o0, o1, negm;
;     float mref = SWA ? m_init : 0.f, lrun = l_init;
; #pragma unroll
;     for (int r = 0; r < 16; ++r) { o0[r] = 0.f; o1[r] = 0.f; negm[r] = -mref; }
.LBB0_1034:
	s_lshr_b32 s14, s13, 4
	s_and_b32 s14, s14, 7
	s_lshl_b32 s20, s14, 7
	v_add_u32_e32 v6, s19, v236
	s_lshl_b32 s12, s12, 6
	s_lshl_b32 s14, s14, 22
	v_lshl_or_b32 v206, v6, 1, s4
	s_or_b32 s4, s4, s20
	v_mov_b32_e32 v6, s4
	s_add_u32 s4, s14, s6
	v_mov_b32_e32 v207, s5
	v_mov_b32_e32 v7, s5
	s_addc_u32 s5, 0, s7
	v_mov_b32_e32 v16, v1
	v_mov_b32_e32 v17, v1
	v_lshl_add_u64 v[208:209], v[4:5], 1, v[6:7]
	v_lshl_add_u64 v[210:211], v[2:3], 1, s[4:5]
	v_mov_b32_e32 v2, v1
	v_mov_b32_e32 v3, v1
	v_mov_b32_e32 v4, v1
	v_mov_b32_e32 v5, v1
	v_mov_b32_e32 v6, v1
	v_mov_b32_e32 v7, v1
	v_mov_b32_e32 v8, v1
	v_mov_b32_e32 v9, v1
	v_mov_b32_e32 v10, v1
	v_mov_b32_e32 v11, v1
	v_mov_b32_e32 v12, v1
	v_mov_b32_e32 v13, v1
	v_mov_b32_e32 v14, v1
	v_mov_b32_e32 v15, v1
	v_bfrev_b32_e32 v82, 1
	v_mov_b64_e32 v[32:33], v[16:17]
	v_readlane_b32 s24, v254, 54
	s_mov_b32 s4, 0
	s_mov_b32 s20, 0xa000
	s_movk_i32 s19, 0x5000
	v_mov_b32_e32 v239, 0
	s_mov_b32 s21, -2
	v_mov_b64_e32 v[30:31], v[14:15]
	v_mov_b64_e32 v[28:29], v[12:13]
	v_mov_b64_e32 v[26:27], v[10:11]
	v_mov_b64_e32 v[24:25], v[8:9]
	v_mov_b64_e32 v[22:23], v[6:7]
	v_mov_b64_e32 v[20:21], v[4:5]
	v_mov_b64_e32 v[18:19], v[2:3]
	v_mov_b32_e32 v160, 0
	v_mov_b32_e32 v83, v82
	v_mov_b32_e32 v84, v82
	v_mov_b32_e32 v85, v82
	v_mov_b32_e32 v86, v82
	v_mov_b32_e32 v87, v82
	v_mov_b32_e32 v88, v82
	v_mov_b32_e32 v89, v82
	v_mov_b32_e32 v90, v82
	v_mov_b32_e32 v91, v82
	v_mov_b32_e32 v92, v82
	v_mov_b32_e32 v93, v82
	v_mov_b32_e32 v94, v82
	v_mov_b32_e32 v95, v82
	v_mov_b32_e32 v96, v82
	v_mov_b32_e32 v97, v82
	v_readlane_b32 s26, v254, 56
	v_readlane_b32 s27, v254, 57
	v_readlane_b32 s25, v254, 55
	s_mov_b32 s23, 0xf000
	v_readfirstlane_b32 s6, v208
	v_readfirstlane_b32 s7, v209
	v_readfirstlane_b32 s24, v210
	v_readfirstlane_b32 s25, v211
	s_add_u32 s34, s26, s6
	s_addc_u32 s35, s27, s7
	s_add_u32 s34, s34, 0x16020000
	s_addc_u32 s35, s35, 0
	v_subrev_u32_e32 v154, s6, v208
	s_add_u32 s28, s26, s24
	s_addc_u32 s29, s27, s25
	s_add_u32 s28, s28, 0x18000100
	s_addc_u32 s29, s29, 0
	v_subrev_u32_e32 v156, s24, v210
	v_readfirstlane_b32 s6, v206
	v_readfirstlane_b32 s7, v207
	s_nop 1
	s_add_u32 s38, s26, s6
	s_addc_u32 s39, s27, s7
	s_add_u32 s38, s38, 0x7820300
	s_addc_u32 s39, s39, 0
	v_subrev_u32_e32 v158, s6, v206
	s_add_i32 s24, s15, s20
	s_mov_b32 m0, s24
	s_andn2_b64 vcc, exec, s[16:17]
	global_load_lds_dwordx4 v154, s[34:35]
	s_add_i32 m0, s24, 0x3000
	s_nop 0
	global_load_lds_dwordx4 v156, s[28:29]
	s_cbranch_vccnz .LmlaSP_nokr
	s_add_i32 m0, s24, 0x2000
	s_nop 0
	global_load_lds_dwordx4 v158, s[38:39]

.LmlaS_top:
	v_add_u32_e32 v164, s19, v238
	v_add_u32_e32 v165, s4, v238
	ds_read_b128 v[172:175], v164
	ds_read_b128 v[176:179], v164 offset:512
	ds_read_b128 v[180:183], v164 offset:2048
	ds_read_b128 v[184:187], v164 offset:2560
	ds_read_b128 v[188:191], v164 offset:4096
	s_add_i32 s24, s15, s23
	s_mov_b32 m0, s24
	s_andn2_b64 vcc, exec, s[16:17]
	global_load_lds_dwordx4 v154, s[34:35]
	s_add_i32 m0, s24, 0x3000
	s_nop 0
	global_load_lds_dwordx4 v156, s[28:29]
	s_cbranch_vccnz .LmlaSA_nokr
	s_add_i32 m0, s24, 0x2000
	s_nop 0
	global_load_lds_dwordx4 v158, s[38:39]
.LmlaSA_nokr:
	s_add_u32 s34, s34, 0x10000
	s_addc_u32 s35, s35, 0
	s_add_u32 s28, s28, 0x80
	s_addc_u32 s29, s29, 0
	s_add_u32 s38, s38, 0x10000
	s_addc_u32 s39, s39, 0
	s_cmp_eq_u32 s21, -2
	s_cselect_b64 s[6:7], -1, 0
	v_cmp_lt_f32_e32 vcc, s33, v162
	s_or_b64 vcc, s[6:7], vcc
	s_cbranch_vccz .LmlaSA_common
	v_mov_b32_e32 v163, v162
	s_nop 1
	v_permlane32_swap_b32_e32 v162, v163
	v_max_f32_e32 v162, v162, v163
	v_max_f32_e32 v220, 0, v162
	v_cndmask_b32_e64 v220, v220, v162, s[6:7]
	v_exp_f32_e64 v222, -v220
	v_add_f32_e32 v239, v239, v220
	v_pk_add_f32 v[66:67], v[66:67], v[220:221] op_sel_hi:[1,0] neg_lo:[0,1] neg_hi:[0,1]
	v_pk_add_f32 v[68:69], v[68:69], v[220:221] op_sel_hi:[1,0] neg_lo:[0,1] neg_hi:[0,1]
	v_pk_add_f32 v[70:71], v[70:71], v[220:221] op_sel_hi:[1,0] neg_lo:[0,1] neg_hi:[0,1]
	v_pk_add_f32 v[72:73], v[72:73], v[220:221] op_sel_hi:[1,0] neg_lo:[0,1] neg_hi:[0,1]
	v_pk_add_f32 v[74:75], v[74:75], v[220:221] op_sel_hi:[1,0] neg_lo:[0,1] neg_hi:[0,1]
	v_pk_add_f32 v[76:77], v[76:77], v[220:221] op_sel_hi:[1,0] neg_lo:[0,1] neg_hi:[0,1]
	v_pk_add_f32 v[78:79], v[78:79], v[220:221] op_sel_hi:[1,0] neg_lo:[0,1] neg_hi:[0,1]
	v_pk_add_f32 v[80:81], v[80:81], v[220:221] op_sel_hi:[1,0] neg_lo:[0,1] neg_hi:[0,1]
	v_pk_add_f32 v[50:51], v[50:51], v[220:221] op_sel_hi:[1,0] neg_lo:[0,1] neg_hi:[0,1]
	v_pk_add_f32 v[52:53], v[52:53], v[220:221] op_sel_hi:[1,0] neg_lo:[0,1] neg_hi:[0,1]
	v_pk_add_f32 v[54:55], v[54:55], v[220:221] op_sel_hi:[1,0] neg_lo:[0,1] neg_hi:[0,1]
	v_pk_add_f32 v[56:57], v[56:57], v[220:221] op_sel_hi:[1,0] neg_lo:[0,1] neg_hi:[0,1]
	v_pk_add_f32 v[58:59], v[58:59], v[220:221] op_sel_hi:[1,0] neg_lo:[0,1] neg_hi:[0,1]
	v_pk_add_f32 v[60:61], v[60:61], v[220:221] op_sel_hi:[1,0] neg_lo:[0,1] neg_hi:[0,1]
	v_pk_add_f32 v[62:63], v[62:63], v[220:221] op_sel_hi:[1,0] neg_lo:[0,1] neg_hi:[0,1]
	v_pk_add_f32 v[64:65], v[64:65], v[220:221] op_sel_hi:[1,0] neg_lo:[0,1] neg_hi:[0,1]
	v_pk_mul_f32 v[2:3], v[2:3], v[222:223] op_sel_hi:[1,0]
	v_pk_mul_f32 v[4:5], v[4:5], v[222:223] op_sel_hi:[1,0]
	v_pk_mul_f32 v[6:7], v[6:7], v[222:223] op_sel_hi:[1,0]
	v_pk_mul_f32 v[8:9], v[8:9], v[222:223] op_sel_hi:[1,0]
	v_pk_mul_f32 v[10:11], v[10:11], v[222:223] op_sel_hi:[1,0]
	v_pk_mul_f32 v[12:13], v[12:13], v[222:223] op_sel_hi:[1,0]
	v_pk_mul_f32 v[14:15], v[14:15], v[222:223] op_sel_hi:[1,0]
	v_pk_mul_f32 v[16:17], v[16:17], v[222:223] op_sel_hi:[1,0]
	v_pk_mul_f32 v[18:19], v[18:19], v[222:223] op_sel_hi:[1,0]
	v_pk_mul_f32 v[20:21], v[20:21], v[222:223] op_sel_hi:[1,0]
	v_pk_mul_f32 v[22:23], v[22:23], v[222:223] op_sel_hi:[1,0]
	v_pk_mul_f32 v[24:25], v[24:25], v[222:223] op_sel_hi:[1,0]
	v_pk_mul_f32 v[26:27], v[26:27], v[222:223] op_sel_hi:[1,0]
	v_pk_mul_f32 v[28:29], v[28:29], v[222:223] op_sel_hi:[1,0]
	v_pk_mul_f32 v[30:31], v[30:31], v[222:223] op_sel_hi:[1,0]
	v_pk_mul_f32 v[32:33], v[32:33], v[222:223] op_sel_hi:[1,0]
	v_mul_f32_e32 v160, v160, v222
	v_xor_b32_e32 v82, 0x80000000, v239
	v_mov_b32_e32 v83, v82
	v_mov_b32_e32 v84, v82
	v_mov_b32_e32 v85, v82
	v_mov_b32_e32 v86, v82
	v_mov_b32_e32 v87, v82
	v_mov_b32_e32 v88, v82
	v_mov_b32_e32 v89, v82
	v_mov_b32_e32 v90, v82
	v_mov_b32_e32 v91, v82
	v_mov_b32_e32 v92, v82
	v_mov_b32_e32 v93, v82
	v_mov_b32_e32 v94, v82
	v_mov_b32_e32 v95, v82
	v_mov_b32_e32 v96, v82
	v_mov_b32_e32 v97, v82
	s_nop 1

.LmlaSA_wd:
	s_barrier
	v_add_u32_e32 v164, s20, v238
	v_add_u32_e32 v165, s19, v238
	ds_read_b128 v[172:175], v164
	ds_read_b128 v[176:179], v164 offset:512
	ds_read_b128 v[180:183], v164 offset:2048
	ds_read_b128 v[184:187], v164 offset:2560
	ds_read_b128 v[188:191], v164 offset:4096
	s_add_i32 s24, s18, s4
	s_mov_b32 m0, s24
	s_andn2_b64 vcc, exec, s[16:17]
	global_load_lds_dwordx4 v154, s[34:35]
	s_add_i32 m0, s24, 0x3000
	s_nop 0
	global_load_lds_dwordx4 v156, s[28:29]
	s_cbranch_vccnz .LmlaSB_nokr
	s_add_i32 m0, s24, 0x2000
	s_nop 0
	global_load_lds_dwordx4 v158, s[38:39]
.LmlaSB_nokr:
	s_add_u32 s34, s34, 0x10000
	s_addc_u32 s35, s35, 0
	s_add_u32 s28, s28, 0x80
	s_addc_u32 s29, s29, 0
	s_add_u32 s38, s38, 0x10000
	s_addc_u32 s39, s39, 0
	v_cmp_lt_f32_e32 vcc, s33, v162
	s_cbranch_vccz .LmlaSB_common
	v_mov_b32_e32 v163, v162
	s_nop 1
	v_permlane32_swap_b32_e32 v162, v163
	v_max_f32_e32 v162, v162, v163
	v_max_f32_e32 v220, 0, v162
	v_exp_f32_e64 v222, -v220
	v_add_f32_e32 v239, v239, v220
	v_pk_add_f32 v[98:99], v[98:99], v[220:221] op_sel_hi:[1,0] neg_lo:[0,1] neg_hi:[0,1]
	v_pk_add_f32 v[100:101], v[100:101], v[220:221] op_sel_hi:[1,0] neg_lo:[0,1] neg_hi:[0,1]
	v_pk_add_f32 v[102:103], v[102:103], v[220:221] op_sel_hi:[1,0] neg_lo:[0,1] neg_hi:[0,1]
	v_pk_add_f32 v[104:105], v[104:105], v[220:221] op_sel_hi:[1,0] neg_lo:[0,1] neg_hi:[0,1]
	v_pk_add_f32 v[106:107], v[106:107], v[220:221] op_sel_hi:[1,0] neg_lo:[0,1] neg_hi:[0,1]
	v_pk_add_f32 v[108:109], v[108:109], v[220:221] op_sel_hi:[1,0] neg_lo:[0,1] neg_hi:[0,1]
	v_pk_add_f32 v[110:111], v[110:111], v[220:221] op_sel_hi:[1,0] neg_lo:[0,1] neg_hi:[0,1]
	v_pk_add_f32 v[112:113], v[112:113], v[220:221] op_sel_hi:[1,0] neg_lo:[0,1] neg_hi:[0,1]
	v_pk_add_f32 v[114:115], v[114:115], v[220:221] op_sel_hi:[1,0] neg_lo:[0,1] neg_hi:[0,1]
	v_pk_add_f32 v[116:117], v[116:117], v[220:221] op_sel_hi:[1,0] neg_lo:[0,1] neg_hi:[0,1]
	v_pk_add_f32 v[118:119], v[118:119], v[220:221] op_sel_hi:[1,0] neg_lo:[0,1] neg_hi:[0,1]
	v_pk_add_f32 v[120:121], v[120:121], v[220:221] op_sel_hi:[1,0] neg_lo:[0,1] neg_hi:[0,1]
	v_pk_add_f32 v[122:123], v[122:123], v[220:221] op_sel_hi:[1,0] neg_lo:[0,1] neg_hi:[0,1]
	v_pk_add_f32 v[124:125], v[124:125], v[220:221] op_sel_hi:[1,0] neg_lo:[0,1] neg_hi:[0,1]
	v_pk_add_f32 v[126:127], v[126:127], v[220:221] op_sel_hi:[1,0] neg_lo:[0,1] neg_hi:[0,1]
	v_pk_add_f32 v[128:129], v[128:129], v[220:221] op_sel_hi:[1,0] neg_lo:[0,1] neg_hi:[0,1]
	v_pk_mul_f32 v[2:3], v[2:3], v[222:223] op_sel_hi:[1,0]
	v_pk_mul_f32 v[4:5], v[4:5], v[222:223] op_sel_hi:[1,0]
	v_pk_mul_f32 v[6:7], v[6:7], v[222:223] op_sel_hi:[1,0]
	v_pk_mul_f32 v[8:9], v[8:9], v[222:223] op_sel_hi:[1,0]
	v_pk_mul_f32 v[10:11], v[10:11], v[222:223] op_sel_hi:[1,0]
	v_pk_mul_f32 v[12:13], v[12:13], v[222:223] op_sel_hi:[1,0]
	v_pk_mul_f32 v[14:15], v[14:15], v[222:223] op_sel_hi:[1,0]
	v_pk_mul_f32 v[16:17], v[16:17], v[222:223] op_sel_hi:[1,0]
	v_pk_mul_f32 v[18:19], v[18:19], v[222:223] op_sel_hi:[1,0]
	v_pk_mul_f32 v[20:21], v[20:21], v[222:223] op_sel_hi:[1,0]
	v_pk_mul_f32 v[22:23], v[22:23], v[222:223] op_sel_hi:[1,0]
	v_pk_mul_f32 v[24:25], v[24:25], v[222:223] op_sel_hi:[1,0]
	v_pk_mul_f32 v[26:27], v[26:27], v[222:223] op_sel_hi:[1,0]
	v_pk_mul_f32 v[28:29], v[28:29], v[222:223] op_sel_hi:[1,0]
	v_pk_mul_f32 v[30:31], v[30:31], v[222:223] op_sel_hi:[1,0]
	v_pk_mul_f32 v[32:33], v[32:33], v[222:223] op_sel_hi:[1,0]
	v_mul_f32_e32 v160, v160, v222
	v_xor_b32_e32 v82, 0x80000000, v239
	v_mov_b32_e32 v83, v82
	v_mov_b32_e32 v84, v82
	v_mov_b32_e32 v85, v82
	v_mov_b32_e32 v86, v82
	v_mov_b32_e32 v87, v82
	v_mov_b32_e32 v88, v82
	v_mov_b32_e32 v89, v82
	v_mov_b32_e32 v90, v82
	v_mov_b32_e32 v91, v82
	v_mov_b32_e32 v92, v82
	v_mov_b32_e32 v93, v82
	v_mov_b32_e32 v94, v82
	v_mov_b32_e32 v95, v82
	v_mov_b32_e32 v96, v82
	v_mov_b32_e32 v97, v82
	s_nop 1
.LmlaSB_common:
	s_waitcnt lgkmcnt(4)
	v_mfma_f32_32x32x16_bf16 v[66:81], v[172:175], v[150:153], v[82:97]
	ds_read_b128 v[192:195], v164 offset:4608
	v_exp_f32_e32 v98, v98
	v_exp_f32_e32 v99, v99
	v_exp_f32_e32 v100, v100
	s_waitcnt lgkmcnt(4)
	v_mfma_f32_32x32x16_bf16 v[50:65], v[176:179], v[150:153], v[82:97]
	ds_read_b128 v[240:243], v164 offset:6144
	v_exp_f32_e32 v101, v101
	v_exp_f32_e32 v102, v102
	v_exp_f32_e32 v103, v103
	s_waitcnt lgkmcnt(4)
	v_mfma_f32_32x32x16_bf16 v[66:81], v[180:183], v[146:149], v[66:81]
	ds_read_b128 v[244:247], v164 offset:6656
	v_exp_f32_e32 v104, v104
	v_exp_f32_e32 v105, v105
	v_cvt_pk_bf16_f32 v34, v98, v99
	v_cvt_pk_bf16_f32 v35, v100, v101
	s_waitcnt lgkmcnt(4)
	v_mfma_f32_32x32x16_bf16 v[50:65], v[184:187], v[146:149], v[50:65]
	ds_read_b128 v[248:251], v164 offset:8192
	v_exp_f32_e32 v106, v106
	v_exp_f32_e32 v107, v107
	v_cvt_pk_bf16_f32 v36, v102, v103
	v_cvt_pk_bf16_f32 v37, v104, v105
	s_waitcnt lgkmcnt(4)
	v_mfma_f32_32x32x16_bf16 v[66:81], v[188:191], v[142:145], v[66:81]
	ds_read_b128 v[172:175], v164 offset:8704
	v_exp_f32_e32 v108, v108
	v_exp_f32_e32 v109, v109
	v_exp_f32_e32 v110, v110
	s_waitcnt lgkmcnt(4)
	v_mfma_f32_32x32x16_bf16 v[50:65], v[192:195], v[142:145], v[50:65]
	ds_read_b128 v[176:179], v164 offset:10240
	v_exp_f32_e32 v111, v111
	v_exp_f32_e32 v112, v112
	v_exp_f32_e32 v113, v113
	s_waitcnt lgkmcnt(4)
	v_mfma_f32_32x32x16_bf16 v[66:81], v[240:243], v[138:141], v[66:81]
	ds_read_b128 v[180:183], v164 offset:10752
	v_exp_f32_e32 v114, v114
	v_exp_f32_e32 v115, v115
	v_cvt_pk_bf16_f32 v38, v106, v107
	v_cvt_pk_bf16_f32 v39, v108, v109
	s_waitcnt lgkmcnt(4)
	v_mfma_f32_32x32x16_bf16 v[50:65], v[244:247], v[138:141], v[50:65]
	ds_read_b128 v[184:187], v165 offset:12288
	v_exp_f32_e32 v116, v116
	v_exp_f32_e32 v117, v117
	v_cvt_pk_bf16_f32 v40, v110, v111
	v_cvt_pk_bf16_f32 v41, v112, v113
	s_waitcnt lgkmcnt(4)
	v_mfma_f32_32x32x16_bf16 v[66:81], v[248:251], v[134:137], v[66:81]
	ds_read_b128 v[188:191], v165 offset:12800
	v_exp_f32_e32 v118, v118
	v_exp_f32_e32 v119, v119
	v_exp_f32_e32 v120, v120
	s_waitcnt lgkmcnt(4)
	v_mfma_f32_32x32x16_bf16 v[50:65], v[172:175], v[134:137], v[50:65]
	ds_read_b128 v[192:195], v165 offset:14336
	v_exp_f32_e32 v121, v121
	v_exp_f32_e32 v122, v122
	v_cvt_pk_bf16_f32 v42, v114, v115
	v_cvt_pk_bf16_f32 v43, v116, v117
	s_waitcnt lgkmcnt(4)
	v_mfma_f32_32x32x16_bf16 v[66:81], v[176:179], v[130:133], v[66:81]
	ds_read_b128 v[240:243], v165 offset:14848
	v_exp_f32_e32 v123, v123
	v_exp_f32_e32 v124, v124
	v_cvt_pk_bf16_f32 v44, v118, v119
	v_cvt_pk_bf16_f32 v45, v120, v121
	s_waitcnt lgkmcnt(4)
	v_mfma_f32_32x32x16_bf16 v[50:65], v[180:183], v[130:133], v[50:65]
	ds_read_b128 v[244:247], v165 offset:16384
	v_exp_f32_e32 v125, v125
	v_exp_f32_e32 v126, v126
	v_exp_f32_e32 v127, v127
	s_waitcnt lgkmcnt(4)
	v_mfma_f32_32x32x16_bf16 v[2:17], v[184:187], v[34:37], v[2:17]
	ds_read_b128 v[248:251], v165 offset:16896
	v_exp_f32_e32 v128, v128
	v_exp_f32_e32 v129, v129
	v_cvt_pk_bf16_f32 v46, v122, v123
	v_cvt_pk_bf16_f32 v47, v124, v125
	s_waitcnt lgkmcnt(4)
	v_mfma_f32_32x32x16_bf16 v[18:33], v[188:191], v[34:37], v[18:33]
	ds_read_b128 v[172:175], v165 offset:18432
	v_cvt_pk_bf16_f32 v48, v126, v127
	v_cvt_pk_bf16_f32 v49, v128, v129
	v_add_f32_e32 v166, v98, v99
	v_add_f32_e32 v167, v100, v101
	v_add_f32_e32 v168, v102, v103
	v_add_f32_e32 v169, v104, v105
	s_waitcnt lgkmcnt(4)
	v_mfma_f32_32x32x16_bf16 v[2:17], v[192:195], v[38:41], v[2:17]
	ds_read_b128 v[176:179], v165 offset:18944
	v_add_f32_e32 v166, v166, v106
	v_add_f32_e32 v167, v167, v107
	v_add_f32_e32 v168, v168, v108
	v_add_f32_e32 v169, v169, v109
	v_max3_f32 v162, v66, v67, v68
	v_max3_f32 v163, v50, v51, v52
	s_waitcnt lgkmcnt(4)
	v_mfma_f32_32x32x16_bf16 v[18:33], v[240:243], v[38:41], v[18:33]
	v_add_f32_e32 v166, v166, v110
	v_add_f32_e32 v167, v167, v111
	v_add_f32_e32 v168, v168, v112
	v_add_f32_e32 v169, v169, v113
	v_max3_f32 v162, v162, v69, v70
	v_max3_f32 v163, v163, v53, v54
	s_waitcnt lgkmcnt(3)
	v_mfma_f32_32x32x16_bf16 v[2:17], v[244:247], v[42:45], v[2:17]
	v_add_f32_e32 v166, v166, v114
	v_add_f32_e32 v167, v167, v115
	v_add_f32_e32 v168, v168, v116
	v_add_f32_e32 v169, v169, v117
	v_max3_f32 v162, v162, v71, v72
	v_max3_f32 v163, v163, v55, v56
	s_waitcnt lgkmcnt(2)
	v_mfma_f32_32x32x16_bf16 v[18:33], v[248:251], v[42:45], v[18:33]
	v_add_f32_e32 v166, v166, v118
	v_add_f32_e32 v167, v167, v119
	v_add_f32_e32 v168, v168, v120
	v_add_f32_e32 v169, v169, v121
	v_max3_f32 v162, v162, v73, v74
	v_max3_f32 v163, v163, v57, v58
	s_waitcnt lgkmcnt(1)
	v_mfma_f32_32x32x16_bf16 v[2:17], v[172:175], v[46:49], v[2:17]
	v_add_f32_e32 v166, v166, v122
	v_add_f32_e32 v167, v167, v123
	v_add_f32_e32 v168, v168, v124
	v_add_f32_e32 v169, v169, v125
	v_max3_f32 v162, v162, v75, v76
	v_max3_f32 v163, v163, v59, v60
	s_waitcnt lgkmcnt(0)
	v_mfma_f32_32x32x16_bf16 v[18:33], v[176:179], v[46:49], v[18:33]
	v_add_f32_e32 v166, v166, v126
	v_add_f32_e32 v167, v167, v127
	v_add_f32_e32 v168, v168, v128
	v_add_f32_e32 v169, v169, v129
	v_max3_f32 v162, v162, v77, v78
	v_max3_f32 v163, v163, v61, v62
	v_max3_f32 v162, v162, v79, v80
	v_max3_f32 v163, v163, v63, v64
	v_add_f32_e32 v166, v166, v167
	v_add_f32_e32 v168, v168, v169
	v_add_f32_e32 v166, v166, v168
	v_add_f32_e32 v160, v160, v166
	v_max3_f32 v162, v162, v81, v65
	v_max_f32_e32 v162, v162, v163
	s_add_i32 s21, s21, 2
	s_andn2_b64 vcc, exec, s[16:17]
	s_cbranch_vccnz .LmlaSB_w2
	s_waitcnt vmcnt(3)
	s_branch .LmlaSB_wd
